# M2 queue: weight-conversion items interleaved 1:1 with NSA items (index remap) instead of all at the end
# baseline (speedup 1.0000x reference)
; __global__ void __launch_bounds__(NT, 2) mega(Params p) {
;     ...
;             for (int it = c; it < n_tot; ) { int r = it;
;                 unsigned nxt_it = 0u; if (threadIdx.x == 0) nxt_it = G + atomicAdd(ctr, 1u);
;                 if (r < N_MB2) { if (MIX_MASK & 2) mamba2_item(p, l, r, lds); }
;                 else if ((r -= N_MB2) < N_ATT) { const int qt = 31 - (r >> 4), bg = r & 15; if (MIX_MASK & 4) nsa_item(p, l, (bg << 5) | qt, lds); }
;                 else convert_wg_item(p, l, r - N_ATT, lds);
.LBB0_1663:
	s_cmpk_lt_i32 s88, 0x80
	s_cbranch_scc1 .Lmy_m2_nr
	v_readlane_b32 s101, v254, 9
	s_add_i32 s100, s88, 0xffffff80
	s_nop 1
	s_addk_i32 s101, 0xfd80
	s_lshl_b32 vcc_lo, s101, 1
	s_cmp_lt_u32 s100, vcc_lo
	s_cbranch_scc0 .Lmy_m2_tailmap
	s_lshr_b32 vcc_lo, s100, 1
	s_movk_i32 vcc_hi, 0x80
	s_bitcmp1_b32 s100, 0
	s_cselect_b32 vcc_hi, 0x280, vcc_hi
	s_add_i32 s88, vcc_lo, vcc_hi
	s_branch .Lmy_m2_nr
.Lmy_m2_tailmap:
	s_sub_i32 s88, s88, s101
